# baseline (speedup 1.0000x reference)
; DEV void finishSM(f32x16& p0, f32x16& p1, float alpha, float& l_reg, bf16x8& pa0, bf16x8& pa1, bf16x8& pa2, bf16x8& pa3) {
; #pragma unroll
;   for (int r = 0; r < 16; ++r) p1[r] = __builtin_amdgcn_exp2f(p1[r]);
;   float ps = 0;
; #pragma unroll
;   for (int r = 0; r < 16; ++r) ps += p0[r];
; #pragma unroll
;   for (int r = 0; r < 16; ++r) ps += p1[r];
;   { auto rr = __builtin_amdgcn_permlane32_swap(__float_as_uint(ps), __float_as_uint(ps), false, false);
;     ps = __uint_as_float(rr[0]) + __uint_as_float(rr[1]); }
;   l_reg = l_reg * alpha + ps;
;     ...
;   PK4(p0, 0, pa0); PK4(p0, 8, pa1); PK4(p1, 0, pa2); PK4(p1, 8, pa3);
; DEV void qkt(f32x16& p0, f32x16& p1, const char* Ks, const char* KPs, const bf16x8* qr, const char* qpl, int r32, int hi) {
;   p0 = f32x16{}; p1 = f32x16{};
; #pragma unroll
;   for (int d0 = 0; d0 < 8; ++d0) { int cb = (d0 * 16 + hi * 8) * 2;
;     bf16x8 b0 = *reinterpret_cast<const bf16x8*>(Ks + KSWZ(r32, cb));
;     bf16x8 b1 = *reinterpret_cast<const bf16x8*>(Ks + KSWZ(32 + r32, cb));
;     bf16x8 qq = d0 < NQR ? qr[d0 < NQR ? d0 : 0] : *reinterpret_cast<const bf16x8*>(qpl + (d0 - NQR) * 1024);
;     p0 = __builtin_amdgcn_mfma_f32_32x32x16_bf16(b0, qq, p0, 0, 0, 0);
;     p1 = __builtin_amdgcn_mfma_f32_32x32x16_bf16(b1, qq, p1, 0, 0, 0); }
; #pragma unroll
;   for (int d1 = 0; d1 < 4; ++d1) { int cb = (d1 * 16 + hi * 8) * 2;
;     bf16x8 b0 = *reinterpret_cast<const bf16x8*>(KPs + KPSWZ(r32, cb));
;     bf16x8 b1 = *reinterpret_cast<const bf16x8*>(KPs + KPSWZ(32 + r32, cb));
;     bf16x8 qp = *reinterpret_cast<const bf16x8*>(qpl + (8 - NQR + d1) * 1024);
;     p0 = __builtin_amdgcn_mfma_f32_32x32x16_bf16(b0, qp, p0, 0, 0, 0);
;     p1 = __builtin_amdgcn_mfma_f32_32x32x16_bf16(b1, qp, p1, 0, 0, 0); }
; }
.LBB0_304:
	ds_read_b128 v[64:67], v159 offset:49152
	ds_read_b128 v[68:71], v159 offset:57344
	ds_read_b128 v[188:191], v162 offset:49152
	ds_read_b128 v[202:205], v162 offset:57344
	s_waitcnt vmcnt(0)
	ds_write_b128 v154, v[238:241] offset:16384
	ds_write_b128 v155, v[242:245] offset:16384
	s_mov_b32 s0, 0x40000
	v_add_co_u32_e32 v224, vcc, s0, v142
	s_nop 1
	v_addc_co_u32_e32 v225, vcc, 0, v143, vcc
	global_load_dwordx4 v[226:229], v[142:143], off
	global_load_dwordx4 v[230:233], v[224:225], off
	global_load_dwordx4 v[234:237], v[140:141], off
	global_load_dwordx4 v[238:241], v[142:143], off offset:256
	global_load_dwordx4 v[242:245], v[224:225], off offset:256
	v_add_f32_e32 v133, 0, v196
	v_add_f32_e32 v133, v199, v133
	s_waitcnt lgkmcnt(5)
	v_mfma_f32_32x32x16_bf16 v[80:95], v[64:67], v[108:111], 0
	v_add_f32_e32 v133, v197, v133
	v_add_f32_e32 v133, v200, v133
	v_add_f32_e32 v133, v198, v133
	v_add_f32_e32 v133, v201, v133
	v_add_f32_e32 v133, v194, v133
	v_add_f32_e32 v133, v195, v133
	v_add_f32_e32 v133, v134, v133
	s_waitcnt lgkmcnt(4)
	v_mfma_f32_32x32x16_bf16 v[64:79], v[68:71], v[108:111], 0
	v_add_f32_e32 v133, v192, v133
	v_add_f32_e32 v133, v135, v133
	v_add_f32_e32 v133, v193, v133
	v_exp_f32_e32 v126, v126
	v_add_f32_e32 v133, v128, v133
	v_exp_f32_e32 v127, v127
	v_add_f32_e32 v133, v130, v133
	s_waitcnt lgkmcnt(0)
	v_mfma_f32_32x32x16_bf16 v[64:79], v[202:205], v[104:107], v[64:79]
	v_exp_f32_e32 v124, v124
	v_add_f32_e32 v133, v129, v133
	v_exp_f32_e32 v125, v125
	v_add_f32_e32 v133, v131, v133
	v_or_b32_e32 v187, 0x12000, v175
	v_exp_f32_e32 v120, v120
	v_add_f32_e32 v133, v126, v133
	v_mfma_f32_32x32x16_bf16 v[80:95], v[188:191], v[104:107], v[80:95]
	ds_read_b128 v[188:191], v163 offset:49152
	ds_read_b128 v[202:205], v163 offset:57344
	v_exp_f32_e32 v121, v121
	v_add_f32_e32 v133, v127, v133
	v_exp_f32_e32 v116, v116
	v_add_f32_e32 v133, v124, v133
	v_exp_f32_e32 v117, v117
	v_add_f32_e32 v133, v125, v133
	s_waitcnt lgkmcnt(0)
	v_mfma_f32_32x32x16_bf16 v[64:79], v[202:205], v[100:103], v[64:79]
	v_exp_f32_e32 v112, v112
	v_add_f32_e32 v133, v120, v133
	v_exp_f32_e32 v113, v113
	v_add_f32_e32 v133, v121, v133
	v_exp_f32_e32 v122, v122
	v_add_f32_e32 v133, v116, v133
	v_exp_f32_e32 v123, v123
	v_mfma_f32_32x32x16_bf16 v[80:95], v[188:191], v[100:103], v[80:95]
	ds_read_b128 v[188:191], v166 offset:49152
	ds_read_b128 v[202:205], v166 offset:57344
	v_add_f32_e32 v133, v117, v133
	v_exp_f32_e32 v118, v118
	v_add_f32_e32 v133, v112, v133
	v_exp_f32_e32 v119, v119
	v_add_f32_e32 v133, v113, v133
	v_exp_f32_e32 v114, v114
	s_waitcnt lgkmcnt(0)
	v_mfma_f32_32x32x16_bf16 v[64:79], v[202:205], v[96:99], v[64:79]
	v_add_f32_e32 v133, v122, v133
	v_exp_f32_e32 v115, v115
	v_add_f32_e32 v133, v123, v133
	v_add_f32_e32 v133, v118, v133
	v_add_f32_e32 v133, v119, v133
	v_add_f32_e32 v133, v114, v133
	v_mfma_f32_32x32x16_bf16 v[80:95], v[188:191], v[96:99], v[80:95]
	ds_read_b128 v[188:191], v167 offset:49152
	ds_read_b128 v[202:205], v167 offset:57344
	ds_read_b128 v[206:209], v177
	s_waitcnt lgkmcnt(0)
	v_mfma_f32_32x32x16_bf16 v[64:79], v[202:205], v[206:209], v[64:79]
	v_mfma_f32_32x32x16_bf16 v[80:95], v[188:191], v[206:209], v[80:95]
	ds_read_b128 v[188:191], v168 offset:49152
	ds_read_b128 v[202:205], v168 offset:57344
	ds_read_b128 v[206:209], v177 offset:1024
	s_waitcnt lgkmcnt(0)
	v_mfma_f32_32x32x16_bf16 v[64:79], v[202:205], v[206:209], v[64:79]
	v_mfma_f32_32x32x16_bf16 v[80:95], v[188:191], v[206:209], v[80:95]
	ds_read_b128 v[188:191], v160 offset:49152
	ds_read_b128 v[202:205], v160 offset:57344
	ds_read_b128 v[206:209], v177 offset:2048
	s_waitcnt lgkmcnt(0)
	v_mfma_f32_32x32x16_bf16 v[64:79], v[202:205], v[206:209], v[64:79]
	v_mfma_f32_32x32x16_bf16 v[80:95], v[188:191], v[206:209], v[80:95]
	ds_read_b128 v[188:191], v161 offset:49152
	ds_read_b128 v[202:205], v161 offset:57344
	ds_read_b128 v[206:209], v177 offset:3072
	s_waitcnt lgkmcnt(0)
	v_mfma_f32_32x32x16_bf16 v[64:79], v[202:205], v[206:209], v[64:79]
	v_mfma_f32_32x32x16_bf16 v[80:95], v[188:191], v[206:209], v[80:95]
	ds_read_b128 v[188:191], v184
	ds_read_b128 v[202:205], v185
	ds_read_b128 v[206:209], v177 offset:4096
	s_waitcnt lgkmcnt(0)
	v_mfma_f32_32x32x16_bf16 v[64:79], v[202:205], v[206:209], v[64:79]
	v_mfma_f32_32x32x16_bf16 v[80:95], v[188:191], v[206:209], v[80:95]
	ds_read_b128 v[188:191], v181
	ds_read_b128 v[202:205], v182
	ds_read_b128 v[206:209], v177 offset:5120
	s_waitcnt lgkmcnt(0)
	v_mfma_f32_32x32x16_bf16 v[64:79], v[202:205], v[206:209], v[64:79]
	v_mfma_f32_32x32x16_bf16 v[80:95], v[188:191], v[206:209], v[80:95]
	ds_read_b128 v[188:191], v179
	ds_read_b128 v[202:205], v180
	ds_read_b128 v[206:209], v177 offset:6144
	s_waitcnt lgkmcnt(0)
	v_mfma_f32_32x32x16_bf16 v[64:79], v[202:205], v[206:209], v[64:79]
	ds_read_b128 v[202:205], v187
	v_mfma_f32_32x32x16_bf16 v[80:95], v[188:191], v[206:209], v[80:95]
	v_or_b32_e32 v188, 0x13000, v175
	ds_read_b128 v[206:209], v188
	ds_read_b128 v[210:213], v177 offset:7168
	v_add_f32_e32 v189, v115, v133
	v_mov_b32_e32 v190, v189
	s_nop 1
	v_permlane32_swap_b32_e32 v189, v190
	v_cvt_pk_bf16_f32 v196, v196, v199
	s_waitcnt lgkmcnt(0)
	v_mfma_f32_32x32x16_bf16 v[80:95], v[202:205], v[210:213], v[80:95]
	v_cvt_pk_bf16_f32 v197, v197, v200
	v_cvt_pk_bf16_f32 v198, v198, v201
	v_cvt_pk_bf16_f32 v199, v194, v195
	v_cvt_pk_bf16_f32 v192, v134, v192
	v_cvt_pk_bf16_f32 v193, v135, v193
	v_cvt_pk_bf16_f32 v194, v128, v130
	v_cvt_pk_bf16_f32 v195, v129, v131
	v_mfma_f32_32x32x16_bf16 v[64:79], v[206:209], v[210:213], v[64:79]
	s_waitcnt vmcnt(2)
; #define SBAR() __builtin_amdgcn_sched_barrier(0)
; DEV void partialSM(f32x16& p0, f32x16& p1, float& m_reg, float& mn, float& alpha) {
;   constexpr float C = SCALE * 1.4426950408889634f;
;   float pmax = p0[0];
; #pragma unroll
;   for (int r = 1; r < 16; ++r) pmax = fmaxf(pmax, p0[r]);
; #pragma unroll
;   for (int r = 0; r < 16; ++r) pmax = fmaxf(pmax, p1[r]);
;   { auto rr = __builtin_amdgcn_permlane32_swap(__float_as_uint(pmax), __float_as_uint(pmax), false, false);
;     pmax = fmaxf(__uint_as_float(rr[0]), __uint_as_float(rr[1])); }
;   if (__builtin_expect(__all(pmax - m_reg <= THR / SCALE), 1)) { mn = m_reg; alpha = 1.f; }
;   else { mn = fmaxf(m_reg, pmax); alpha = __builtin_amdgcn_exp2f((m_reg - mn) * C); m_reg = mn; }
;   float mnC = -mn * C;
; #pragma unroll
;   for (int r = 0; r < 16; ++r) p0[r] = fmaf(p0[r], C, mnC);
; #pragma unroll
;   for (int r = 0; r < 16; ++r) p1[r] = fmaf(p1[r], C, mnC);
; #pragma unroll
;   for (int r = 0; r < 16; ++r) p0[r] = __builtin_amdgcn_exp2f(p0[r]);
; }
; template <int OFF> DEV s16x4 tr_read(int vb) {
;   s16x4 r; asm volatile("ds_read_b64_tr_b16 %0, %1 offset:%2" : "=&v"(r) : "v"(vb), "i"(OFF) : "memory"); return r;
; }
; template <int D0> DEV void pv_one(f32x16& od, int vb, bf16x8 pa0, bf16x8 pa1, bf16x8 pa2, bf16x8 pa3) {
;   const s16x4 l0 = tr_read<v_rd_off(D0, 0, 0)>(vb), h0 = tr_read<v_rd_off(D0, 0, 1)>(vb), l1 = tr_read<v_rd_off(D0, 1, 0)>(vb), h1 = tr_read<v_rd_off(D0, 1, 1)>(vb);
;   const s16x4 l2 = tr_read<v_rd_off(D0, 2, 0)>(vb), h2 = tr_read<v_rd_off(D0, 2, 1)>(vb), l3 = tr_read<v_rd_off(D0, 3, 0)>(vb), h3 = tr_read<v_rd_off(D0, 3, 1)>(vb);
;   asm volatile("s_waitcnt lgkmcnt(0)" ::: "memory"); SBAR();
;     ...
;   od = __builtin_amdgcn_mfma_f32_32x32x16_bf16(pa0, PK(l0, h0), od, 0, 0, 0);
;   od = __builtin_amdgcn_mfma_f32_32x32x16_bf16(pa1, PK(l1, h1), od, 0, 0, 0);
;   od = __builtin_amdgcn_mfma_f32_32x32x16_bf16(pa2, PK(l2, h2), od, 0, 0, 0);
;   od = __builtin_amdgcn_mfma_f32_32x32x16_bf16(pa3, PK(l3, h3), od, 0, 0, 0);
;     ...
; }
; DEV void pv_d0(f32x16* o, int vb, bf16x8 pa0, bf16x8 pa1, bf16x8 pa2, bf16x8 pa3) {
;   pv_one<0>(o[0], vb, pa0, pa1, pa2, pa3); pv_one<1>(o[1], vb, pa0, pa1, pa2, pa3); pv_one<2>(o[2], vb, pa0, pa1, pa2, pa3); pv_one<3>(o[3], vb, pa0, pa1, pa2, pa3);
	ds_write_b128 v156, v[226:229] offset:32768
	ds_write_b128 v157, v[230:233] offset:32768
	ds_write_b128 v158, v[234:237]
	ds_read_b64_tr_b16 v[208:209], v153 offset:0
	ds_read_b64_tr_b16 v[210:211], v153 offset:0x800
	ds_read_b64_tr_b16 v[212:213], v153 offset:0x1000
	ds_read_b64_tr_b16 v[214:215], v153 offset:0x1800
	ds_read_b64_tr_b16 v[216:217], v153 offset:0x2000
	ds_read_b64_tr_b16 v[218:219], v153 offset:0x2800
	ds_read_b64_tr_b16 v[220:221], v153 offset:0x3000
	ds_read_b64_tr_b16 v[222:223], v153 offset:0x3800
	v_cvt_pk_bf16_f32 v200, v126, v127
	v_cvt_pk_bf16_f32 v201, v124, v125
	v_cvt_pk_bf16_f32 v202, v120, v121
	v_cvt_pk_bf16_f32 v203, v116, v117
	v_cvt_pk_bf16_f32 v204, v112, v113
	v_cvt_pk_bf16_f32 v205, v122, v123
	v_cvt_pk_bf16_f32 v206, v118, v119
	v_cvt_pk_bf16_f32 v207, v114, v115
	v_permlane32_swap_b32_e32 v196, v198
	v_permlane32_swap_b32_e32 v197, v199
	v_permlane32_swap_b32_e32 v192, v194
	v_permlane32_swap_b32_e32 v193, v195
	v_permlane32_swap_b32_e32 v200, v202
	v_permlane32_swap_b32_e32 v201, v203
	v_permlane32_swap_b32_e32 v204, v206
	v_permlane32_swap_b32_e32 v205, v207
	s_waitcnt lgkmcnt(6)
	s_nop 0
	v_mfma_f32_32x32x16_bf16 v[0:15], v[196:199], v[208:211], v[0:15]
	ds_read_b64_tr_b16 v[208:209], v153 offset:0x200
	ds_read_b64_tr_b16 v[210:211], v153 offset:0xa00
	v_max_f32_e32 v133, v81, v81
	v_max_f32_e32 v134, v80, v80
	v_max_f32_e32 v133, v134, v133
	v_max3_f32 v133, v133, v82, v83
	v_max3_f32 v133, v133, v84, v85
	s_waitcnt lgkmcnt(6)
	v_mfma_f32_32x32x16_bf16 v[0:15], v[192:195], v[212:215], v[0:15]
	ds_read_b64_tr_b16 v[212:213], v153 offset:0x1200
	ds_read_b64_tr_b16 v[214:215], v153 offset:0x1a00
	v_max3_f32 v133, v133, v86, v87
	v_max3_f32 v133, v133, v88, v89
	v_max3_f32 v133, v133, v90, v91
	v_max3_f32 v133, v133, v92, v93
	v_max3_f32 v133, v133, v94, v95
	s_waitcnt lgkmcnt(6)
	v_mfma_f32_32x32x16_bf16 v[0:15], v[200:203], v[216:219], v[0:15]
	ds_read_b64_tr_b16 v[216:217], v153 offset:0x2200
	ds_read_b64_tr_b16 v[218:219], v153 offset:0x2a00
	v_max3_f32 v133, v133, v64, v65
	v_max3_f32 v133, v133, v66, v67
	v_max3_f32 v133, v133, v68, v69
	v_max3_f32 v133, v133, v70, v71
	v_max3_f32 v133, v133, v72, v73
	s_waitcnt lgkmcnt(6)
	v_mfma_f32_32x32x16_bf16 v[0:15], v[204:207], v[220:223], v[0:15]
	ds_read_b64_tr_b16 v[220:221], v153 offset:0x3200
	ds_read_b64_tr_b16 v[222:223], v153 offset:0x3a00
	v_max3_f32 v133, v133, v74, v75
	v_max3_f32 v133, v133, v76, v77
	v_max3_f32 v133, v133, v78, v79
	v_mov_b32_e32 v134, v133
	s_waitcnt lgkmcnt(6)
	v_mfma_f32_32x32x16_bf16 v[48:63], v[196:199], v[208:211], v[48:63]
	ds_read_b64_tr_b16 v[208:209], v153 offset:0x400
	ds_read_b64_tr_b16 v[210:211], v153 offset:0xc00
	s_nop 1
	v_permlane32_swap_b32_e32 v133, v134
	v_max_f32_e32 v134, v134, v134
	v_max_f32_e32 v133, v133, v133
	s_waitcnt lgkmcnt(6)
	v_mfma_f32_32x32x16_bf16 v[48:63], v[192:195], v[212:215], v[48:63]
	ds_read_b64_tr_b16 v[212:213], v153 offset:0x1400
	ds_read_b64_tr_b16 v[214:215], v153 offset:0x1c00
	v_max_f32_e32 v133, v133, v134
	v_sub_f32_e32 v134, v133, v132
	v_cmp_ge_f32_e32 vcc, s72, v134
	v_max_f32_e32 v134, v132, v132
	s_waitcnt lgkmcnt(6)
	v_mfma_f32_32x32x16_bf16 v[48:63], v[200:203], v[216:219], v[48:63]
	ds_read_b64_tr_b16 v[216:217], v153 offset:0x2400
	ds_read_b64_tr_b16 v[218:219], v153 offset:0x2c00
	v_max_f32_e32 v133, v134, v133
	v_sub_f32_e32 v134, v132, v133
	v_mul_f32_e32 v134, 0x3dd53b94, v134
	v_exp_f32_e32 v134, v134
	s_waitcnt lgkmcnt(6)
	v_mfma_f32_32x32x16_bf16 v[48:63], v[204:207], v[220:223], v[48:63]
	ds_read_b64_tr_b16 v[220:221], v153 offset:0x3400
	ds_read_b64_tr_b16 v[222:223], v153 offset:0x3c00
	s_cmp_eq_u64 vcc, exec
	s_cselect_b64 s[4:5], -1, 0
	v_cndmask_b32_e64 v226, v133, v132, s[4:5]
	v_mul_f32_e32 v227, 0xbdd53b94, v226
	s_waitcnt lgkmcnt(6)
	v_mfma_f32_32x32x16_bf16 v[32:47], v[196:199], v[208:211], v[32:47]
	ds_read_b64_tr_b16 v[208:209], v153 offset:0x600
	ds_read_b64_tr_b16 v[210:211], v153 offset:0xe00
	v_fmamk_f32 v80, v80, 0x3dd53b94, v227
	v_fmamk_f32 v81, v81, 0x3dd53b94, v227
	v_fmamk_f32 v82, v82, 0x3dd53b94, v227
	v_fmamk_f32 v83, v83, 0x3dd53b94, v227
	s_waitcnt lgkmcnt(6)
	v_mfma_f32_32x32x16_bf16 v[32:47], v[192:195], v[212:215], v[32:47]
	ds_read_b64_tr_b16 v[212:213], v153 offset:0x1600
	ds_read_b64_tr_b16 v[214:215], v153 offset:0x1e00
	v_fmamk_f32 v84, v84, 0x3dd53b94, v227
	v_fmamk_f32 v85, v85, 0x3dd53b94, v227
	v_fmamk_f32 v86, v86, 0x3dd53b94, v227
	v_fmamk_f32 v87, v87, 0x3dd53b94, v227
	s_waitcnt lgkmcnt(6)
	v_mfma_f32_32x32x16_bf16 v[32:47], v[200:203], v[216:219], v[32:47]
	ds_read_b64_tr_b16 v[216:217], v153 offset:0x2600
	ds_read_b64_tr_b16 v[218:219], v153 offset:0x2e00
	v_fmamk_f32 v88, v88, 0x3dd53b94, v227
	v_fmamk_f32 v89, v89, 0x3dd53b94, v227
	v_fmamk_f32 v90, v90, 0x3dd53b94, v227
	v_fmamk_f32 v91, v91, 0x3dd53b94, v227
	s_waitcnt lgkmcnt(6)
	v_mfma_f32_32x32x16_bf16 v[32:47], v[204:207], v[220:223], v[32:47]
	ds_read_b64_tr_b16 v[220:221], v153 offset:0x3600
	ds_read_b64_tr_b16 v[222:223], v153 offset:0x3e00
	v_fmamk_f32 v92, v92, 0x3dd53b94, v227
	v_fmamk_f32 v93, v93, 0x3dd53b94, v227
	v_fmamk_f32 v94, v94, 0x3dd53b94, v227
	v_fmamk_f32 v95, v95, 0x3dd53b94, v227
	s_waitcnt lgkmcnt(6)
	v_mfma_f32_32x32x16_bf16 v[16:31], v[196:199], v[208:211], v[16:31]
	v_exp_f32_e32 v125, v80
	v_exp_f32_e32 v127, v81
	v_exp_f32_e32 v123, v82
	v_exp_f32_e32 v126, v83
	s_waitcnt lgkmcnt(4)
	v_mfma_f32_32x32x16_bf16 v[16:31], v[192:195], v[212:215], v[16:31]
	v_exp_f32_e32 v122, v84
	v_exp_f32_e32 v124, v85
	v_exp_f32_e32 v120, v86
	v_exp_f32_e32 v121, v87
	s_waitcnt lgkmcnt(2)
	v_mfma_f32_32x32x16_bf16 v[16:31], v[200:203], v[216:219], v[16:31]
	v_exp_f32_e32 v117, v88
	v_exp_f32_e32 v119, v89
	v_exp_f32_e32 v116, v90
	v_exp_f32_e32 v118, v91
	s_waitcnt lgkmcnt(0)
	v_mfma_f32_32x32x16_bf16 v[16:31], v[204:207], v[220:223], v[16:31]
	v_exp_f32_e32 v113, v92
	v_exp_f32_e32 v115, v93
	v_exp_f32_e32 v112, v94
	v_exp_f32_e32 v114, v95
	v_cndmask_b32_e64 v191, v134, 1.0, s[4:5]
	v_cmp_gt_f32_e32 vcc, 1.0, v191
	s_cbranch_vccz .LBB0_308
	s_and_saveexec_b64 s[8:9], s[6:7]
	ds_write_b32 v150, v191 offset:128
	s_or_b64 exec, exec, s[8:9]
	s_waitcnt lgkmcnt(0)
	v_add_u32_e32 v228, v139, v136
	ds_read_b128 v[208:211], v228 offset:224
	ds_read_b128 v[212:215], v228 offset:192
	ds_read_b128 v[216:219], v228 offset:160
	ds_read_b128 v[220:223], v228 offset:128
	s_waitcnt lgkmcnt(3)
	v_pk_mul_f32 v[12:13], v[12:13], v[208:209]
	s_waitcnt lgkmcnt(2)
	v_pk_mul_f32 v[8:9], v[8:9], v[212:213]
	s_waitcnt lgkmcnt(1)
	v_pk_mul_f32 v[4:5], v[4:5], v[216:217]
	v_pk_mul_f32 v[14:15], v[14:15], v[210:211]
	v_pk_mul_f32 v[10:11], v[10:11], v[214:215]
	v_pk_mul_f32 v[6:7], v[6:7], v[218:219]
	s_waitcnt lgkmcnt(0)
	v_pk_mul_f32 v[2:3], v[2:3], v[222:223]
	v_pk_mul_f32 v[0:1], v[0:1], v[220:221]
	v_pk_mul_f32 v[60:61], v[60:61], v[208:209]
	v_pk_mul_f32 v[56:57], v[56:57], v[212:213]
	v_pk_mul_f32 v[52:53], v[52:53], v[216:217]
	v_pk_mul_f32 v[62:63], v[62:63], v[210:211]
	v_pk_mul_f32 v[58:59], v[58:59], v[214:215]
	v_pk_mul_f32 v[54:55], v[54:55], v[218:219]
	v_pk_mul_f32 v[50:51], v[50:51], v[222:223]
	v_pk_mul_f32 v[48:49], v[48:49], v[220:221]
	v_pk_mul_f32 v[44:45], v[44:45], v[208:209]
	v_pk_mul_f32 v[40:41], v[40:41], v[212:213]
	v_pk_mul_f32 v[36:37], v[36:37], v[216:217]
	v_pk_mul_f32 v[46:47], v[46:47], v[210:211]
	v_pk_mul_f32 v[42:43], v[42:43], v[214:215]
	v_pk_mul_f32 v[38:39], v[38:39], v[218:219]
	v_pk_mul_f32 v[34:35], v[34:35], v[222:223]
	v_pk_mul_f32 v[32:33], v[32:33], v[220:221]
	v_pk_mul_f32 v[28:29], v[28:29], v[208:209]
	v_pk_mul_f32 v[24:25], v[24:25], v[212:213]
	v_pk_mul_f32 v[20:21], v[20:21], v[216:217]
	v_pk_mul_f32 v[30:31], v[30:31], v[210:211]
	v_pk_mul_f32 v[26:27], v[26:27], v[214:215]
	v_pk_mul_f32 v[22:23], v[22:23], v[218:219]
	v_pk_mul_f32 v[18:19], v[18:19], v[222:223]
	v_pk_mul_f32 v[16:17], v[16:17], v[220:221]
